# w_in transposes: tile order in blocks of 8 row-tiles x 60 col-tiles
# baseline (speedup 1.0000x reference)
.LBB0_34:
	s_lshr_b32 s4, s20, 5
	s_mul_i32 s4, s4, 0x8889
	s_lshr_b32 s4, s4, 19
	s_mul_i32 s5, s4, 0x1e0
	s_sub_i32 s5, s20, s5
	s_lshl_b32 s4, s4, 3
	s_and_b32 s0, s5, 7
	s_add_i32 s0, s0, s4
	s_lshr_b32 s22, s5, 3
	s_lshl_b32 s22, s22, 8
	s_mul_i32 s4, s0, 0x3c00
	s_add_i32 s22, s22, s4
	s_add_i32 s22, s22, 0xfff58000
	s_mul_i32 s5, s0, 0xffffc400
	s_add_i32 s5, s22, s5
	s_add_i32 s6, s5, 0xa8000
	s_ashr_i32 s7, s6, 31
	s_lshl_b32 s4, s0, 6
	v_mov_b32_e32 v52, v1
	s_lshl_b64 s[6:7], s[6:7], 2
	s_add_u32 s6, s74, s6
	v_lshlrev_b32_e32 v4, 4, v52
	s_addc_u32 s7, s75, s7
	v_and_b32_e32 v4, 0x3f0, v4
	v_ashrrev_i32_e32 v38, 6, v52
	v_add_u32_e32 v53, 0x200, v52
	v_lshl_add_u64 v[34:35], s[6:7], 0, v[4:5]
	v_add_u32_e32 v4, s4, v38
	v_ashrrev_i32_e32 v40, 6, v53
	v_add_u32_e32 v54, 0x400, v52
	v_mad_i64_i32 v[6:7], s[6:7], v4, s19, v[34:35]
	v_add_u32_e32 v4, s4, v40
	v_ashrrev_i32_e32 v42, 6, v54
	v_add_u32_e32 v55, 0x600, v52
	v_mad_i64_i32 v[10:11], s[6:7], v4, s19, v[34:35]
	v_add_u32_e32 v4, s4, v42
	v_ashrrev_i32_e32 v44, 6, v55
	global_load_dwordx4 v[6:9], v[6:7], off
	s_nop 0
	global_load_dwordx4 v[10:13], v[10:11], off
	v_mad_i64_i32 v[14:15], s[6:7], v4, s19, v[34:35]
	v_add_u32_e32 v4, s4, v44
	v_mad_i64_i32 v[18:19], s[6:7], v4, s19, v[34:35]
	v_add_u32_e32 v4, 0x800, v52
	v_ashrrev_i32_e32 v46, 6, v4
	v_add_u32_e32 v4, s4, v46
	global_load_dwordx4 v[14:17], v[14:15], off
	s_nop 0
	global_load_dwordx4 v[18:21], v[18:19], off
	v_mad_i64_i32 v[22:23], s[6:7], v4, s19, v[34:35]
	v_add_u32_e32 v4, 0xa00, v52
	v_ashrrev_i32_e32 v48, 6, v4
	v_add_u32_e32 v4, s4, v48
	v_mad_i64_i32 v[26:27], s[6:7], v4, s19, v[34:35]
	global_load_dwordx4 v[22:25], v[22:23], off
	s_nop 0
	global_load_dwordx4 v[26:29], v[26:27], off
	v_add_u32_e32 v4, 0xc00, v52
	v_ashrrev_i32_e32 v50, 6, v4
	v_add_u32_e32 v4, s4, v50
	v_mad_i64_i32 v[30:31], s[6:7], v4, s19, v[34:35]
	v_add_u32_e32 v4, 0xe00, v52
	v_ashrrev_i32_e32 v56, 6, v4
	v_add_u32_e32 v4, s4, v56
	v_lshlrev_b32_e32 v57, 3, v52
	v_mad_i64_i32 v[34:35], s[6:7], v4, s19, v[34:35]
	v_and_b32_e32 v4, 0x1f8, v57
	global_load_dwordx4 v[30:33], v[30:31], off
	v_mad_u64_u32 v[38:39], s[6:7], v38, s17, v[4:5]
	global_load_dwordx4 v[34:37], v[34:35], off
	v_mad_u64_u32 v[40:41], s[6:7], v40, s17, v[4:5]
	v_mad_u64_u32 v[42:43], s[6:7], v42, s17, v[4:5]
	v_mad_u64_u32 v[44:45], s[6:7], v44, s17, v[4:5]
	v_mad_u64_u32 v[46:47], s[6:7], v46, s17, v[4:5]
	v_mad_u64_u32 v[48:49], s[6:7], v48, s17, v[4:5]
	v_mad_u64_u32 v[50:51], s[6:7], v50, s17, v[4:5]
	s_ashr_i32 s5, s4, 31
	s_lshl_b64 s[4:5], s[4:5], 1
	s_add_u32 s4, s94, s4
	s_addc_u32 s5, s95, s5
	s_mulk_i32 s0, 0x3c00
	s_waitcnt vmcnt(7)
	v_cvt_pk_bf16_f32 v6, v6, v7
	ds_write_b32 v38, v6
	v_cvt_pk_bf16_f32 v6, v8, v9
	ds_write_b32 v38, v6 offset:4
	s_waitcnt vmcnt(6)
	v_cvt_pk_bf16_f32 v6, v10, v11
	ds_write_b32 v40, v6
	v_cvt_pk_bf16_f32 v6, v12, v13
	ds_write_b32 v40, v6 offset:4
	s_waitcnt vmcnt(5)
	v_cvt_pk_bf16_f32 v6, v14, v15
	ds_write_b32 v42, v6
	v_cvt_pk_bf16_f32 v6, v16, v17
	ds_write_b32 v42, v6 offset:4
	s_waitcnt vmcnt(4)
	v_cvt_pk_bf16_f32 v6, v18, v19
	ds_write_b32 v44, v6
	v_cvt_pk_bf16_f32 v6, v20, v21
	ds_write_b32 v44, v6 offset:4
	s_waitcnt vmcnt(3)
	v_cvt_pk_bf16_f32 v6, v22, v23
	ds_write_b32 v46, v6
	v_cvt_pk_bf16_f32 v6, v24, v25
	ds_write_b32 v46, v6 offset:4
	s_waitcnt vmcnt(2)
	v_cvt_pk_bf16_f32 v6, v26, v27
	ds_write_b32 v48, v6
	v_cvt_pk_bf16_f32 v6, v28, v29
	ds_write_b32 v48, v6 offset:4
	s_waitcnt vmcnt(1)
	v_cvt_pk_bf16_f32 v6, v30, v31
	ds_write_b32 v50, v6
	v_cvt_pk_bf16_f32 v6, v32, v33
	ds_write_b32 v50, v6 offset:4
	v_mad_u64_u32 v[6:7], s[6:7], v56, s17, v[4:5]
	s_waitcnt vmcnt(0)
	v_cvt_pk_bf16_f32 v8, v34, v35
	ds_write_b32 v6, v8
	v_cvt_pk_bf16_f32 v4, v36, v37
	ds_write_b32 v6, v4 offset:4
	v_and_b32_e32 v4, 56, v57
	v_mul_u32_u24_e32 v14, 0x204, v4
	v_ashrrev_i32_e32 v12, 3, v52
	v_lshl_add_u32 v6, v12, 1, v14
	s_waitcnt lgkmcnt(0)
	s_barrier
	ds_read_u16 v13, v6
	ds_read_u16 v15, v6 offset:516
	ds_read_u16 v7, v6 offset:1032
	ds_read_u16 v16, v6 offset:1548
	ds_read_u16 v8, v6 offset:2064
	ds_read_u16 v17, v6 offset:2580
	ds_read_u16 v9, v6 offset:3096
	ds_read_u16 v6, v6 offset:3612
	v_lshlrev_b32_e32 v4, 1, v4
	v_lshl_add_u64 v[10:11], s[4:5], 0, v[4:5]
	v_subrev_u32_e32 v4, s0, v12
	v_add_u32_e32 v4, s22, v4
	v_add_u32_e32 v12, 0xa8000, v4
	v_ashrrev_i32_e32 v4, 3, v53
	s_waitcnt lgkmcnt(0)
	v_perm_b32 v9, v6, v9, s18
	v_perm_b32 v6, v15, v13, s18
	v_lshl_add_u32 v13, v4, 1, v14
	v_perm_b32 v8, v17, v8, s18
	v_perm_b32 v7, v16, v7, s18
	ds_read_u16 v15, v13
	ds_read_u16 v16, v13 offset:516
	ds_read_u16 v17, v13 offset:1032
	ds_read_u16 v18, v13 offset:1548
	ds_read_u16 v19, v13 offset:2064
	ds_read_u16 v20, v13 offset:2580
	ds_read_u16 v21, v13 offset:3096
	ds_read_u16 v22, v13 offset:3612
	v_ashrrev_i32_e32 v13, 31, v12
	v_lshlrev_b64 v[12:13], 12, v[12:13]
	v_subrev_u32_e32 v4, s0, v4
	v_lshl_add_u64 v[12:13], v[10:11], 0, v[12:13]
	v_add_u32_e32 v4, s22, v4
	global_store_dwordx4 v[12:13], v[6:9], off
	v_add_u32_e32 v12, 0xa8000, v4
	v_ashrrev_i32_e32 v4, 3, v54
	v_lshl_add_u32 v13, v4, 1, v14
	s_waitcnt lgkmcnt(0)
	v_perm_b32 v9, v22, v21, s18
	v_perm_b32 v8, v20, v19, s18
	v_perm_b32 v7, v18, v17, s18
	v_perm_b32 v6, v16, v15, s18
	ds_read_u16 v15, v13
	ds_read_u16 v16, v13 offset:516
	ds_read_u16 v17, v13 offset:1032
	ds_read_u16 v18, v13 offset:1548
	ds_read_u16 v19, v13 offset:2064
	ds_read_u16 v20, v13 offset:2580
	ds_read_u16 v21, v13 offset:3096
	ds_read_u16 v22, v13 offset:3612
	v_ashrrev_i32_e32 v13, 31, v12
	v_lshlrev_b64 v[12:13], 12, v[12:13]
	v_subrev_u32_e32 v4, s0, v4
	v_lshl_add_u64 v[12:13], v[10:11], 0, v[12:13]
	v_add_u32_e32 v4, s22, v4
	global_store_dwordx4 v[12:13], v[6:9], off
	v_add_u32_e32 v12, 0xa8000, v4
	v_ashrrev_i32_e32 v4, 3, v55
	v_lshl_add_u32 v13, v4, 1, v14
	s_waitcnt lgkmcnt(0)
	v_perm_b32 v9, v22, v21, s18
	v_perm_b32 v8, v20, v19, s18
	v_perm_b32 v7, v18, v17, s18
	v_perm_b32 v6, v16, v15, s18
	ds_read_u16 v14, v13
	ds_read_u16 v15, v13 offset:516
	ds_read_u16 v16, v13 offset:1032
	ds_read_u16 v17, v13 offset:1548
	ds_read_u16 v18, v13 offset:2064
	ds_read_u16 v19, v13 offset:2580
	ds_read_u16 v20, v13 offset:3096
	ds_read_u16 v21, v13 offset:3612
	v_ashrrev_i32_e32 v13, 31, v12
	v_lshlrev_b64 v[12:13], 12, v[12:13]
	v_subrev_u32_e32 v4, s0, v4
	v_lshl_add_u64 v[12:13], v[10:11], 0, v[12:13]
	v_add_u32_e32 v4, s22, v4
	global_store_dwordx4 v[12:13], v[6:9], off
	v_add_u32_e32 v12, 0xa8000, v4
	v_ashrrev_i32_e32 v13, 31, v12
	v_lshlrev_b64 v[12:13], 12, v[12:13]
	s_waitcnt lgkmcnt(0)
	v_perm_b32 v9, v21, v20, s18
	v_perm_b32 v8, v19, v18, s18
	v_perm_b32 v7, v17, v16, s18
	v_perm_b32 v6, v15, v14, s18
	v_lshl_add_u64 v[10:11], v[10:11], 0, v[12:13]
	global_store_dwordx4 v[10:11], v[6:9], off
	s_barrier
	s_branch .LBB0_23

.LBB0_88:
	s_lshr_b32 s0, s5, 5
	s_mul_i32 s0, s0, 0x8889
	s_lshr_b32 s0, s0, 19
	s_mul_i32 s1, s0, 0x1e0
	s_sub_i32 s1, s5, s1
	s_lshl_b32 s0, s0, 3
	s_and_b32 s6, s1, 7
	s_add_i32 s6, s6, s0
	s_lshr_b32 s4, s1, 3
	s_lshl_b32 s4, s4, 8
	s_mul_i32 s1, s6, 0x3c00
	s_add_i32 s4, s4, s1
	s_mul_i32 s1, s6, 0xffffc400
	s_add_i32 s8, s4, s1
	s_ashr_i32 s9, s8, 31
	s_lshl_b32 s0, s6, 6
	v_mov_b32_e32 v7, v1
	s_lshl_b64 s[8:9], s[8:9], 2
	s_add_u32 s8, s17, s8
	v_lshlrev_b32_e32 v2, 4, v7
	v_add_u32_e32 v24, 0x800, v7
	s_addc_u32 s9, s20, s9
	v_and_b32_e32 v194, 0x3f0, v2
	v_ashrrev_i32_e32 v40, 6, v7
	v_ashrrev_i32_e32 v44, 6, v24
	v_lshl_add_u64 v[2:3], s[8:9], 0, v[194:195]
	v_add_u32_e32 v4, s0, v40
	v_add_u32_e32 v41, 0x200, v7
	v_add_u32_e32 v24, s0, v44
	v_add_u32_e32 v28, 0xa00, v7
	v_mad_i64_i32 v[4:5], s[8:9], v4, s25, v[2:3]
	v_ashrrev_i32_e32 v42, 6, v41
	v_mad_i64_i32 v[24:25], s[8:9], v24, s25, v[2:3]
	v_ashrrev_i32_e32 v45, 6, v28
	global_load_dwordx4 v[8:11], v[4:5], off
	v_add_u32_e32 v6, 0x400, v7
	global_load_dwordx4 v[24:27], v[24:25], off
	v_add_u32_e32 v4, s0, v42
	v_add_u32_e32 v28, s0, v45
	v_add_u32_e32 v32, 0xc00, v7
	v_mad_i64_i32 v[4:5], s[8:9], v4, s25, v[2:3]
	v_ashrrev_i32_e32 v43, 6, v6
	v_mad_i64_i32 v[28:29], s[8:9], v28, s25, v[2:3]
	v_ashrrev_i32_e32 v46, 6, v32
	global_load_dwordx4 v[12:15], v[4:5], off
	v_add_u32_e32 v32, s0, v46
	global_load_dwordx4 v[28:31], v[28:29], off
	v_add_u32_e32 v4, s0, v43
	v_mad_i64_i32 v[4:5], s[8:9], v4, s25, v[2:3]
	v_mad_i64_i32 v[32:33], s[8:9], v32, s25, v[2:3]
	global_load_dwordx4 v[16:19], v[4:5], off
	v_add_u32_e32 v36, 0xe00, v7
	global_load_dwordx4 v[32:35], v[32:33], off
	v_add_u32_e32 v4, 0x600, v7
	v_ashrrev_i32_e32 v5, 6, v4
	v_ashrrev_i32_e32 v47, 6, v36
	v_add_u32_e32 v20, s0, v5
	v_add_u32_e32 v36, s0, v47
	v_mad_i64_i32 v[20:21], s[8:9], v20, s25, v[2:3]
	v_mad_i64_i32 v[2:3], s[8:9], v36, s25, v[2:3]
	v_lshlrev_b32_e32 v48, 3, v7
	global_load_dwordx4 v[20:23], v[20:21], off
	v_ashrrev_i32_e32 v7, 3, v7
	global_load_dwordx4 v[36:39], v[2:3], off
	v_and_b32_e32 v2, 0x1f8, v48
	s_waitcnt vmcnt(0)
	v_cvt_pk_bf16_f32 v3, v8, v9
	s_ashr_i32 s1, s0, 31
	v_mad_u64_u32 v[8:9], s[8:9], v40, s33, v[2:3]
	ds_write_b32 v8, v3
	v_cvt_pk_bf16_f32 v3, v10, v11
	ds_write_b32 v8, v3 offset:4
	s_waitcnt vmcnt(5)
	v_cvt_pk_bf16_f32 v3, v12, v13
	s_mulk_i32 s6, 0x3c00
	v_mad_u64_u32 v[8:9], s[8:9], v42, s33, v[2:3]
	ds_write_b32 v8, v3
	v_cvt_pk_bf16_f32 v3, v14, v15
	ds_write_b32 v8, v3 offset:4
	s_waitcnt vmcnt(3)
	v_cvt_pk_bf16_f32 v3, v16, v17
	s_lshl_b64 s[0:1], s[0:1], 1
	v_mad_u64_u32 v[8:9], s[8:9], v43, s33, v[2:3]
	ds_write_b32 v8, v3
	v_cvt_pk_bf16_f32 v3, v18, v19
	ds_write_b32 v8, v3 offset:4
	s_waitcnt vmcnt(1)
	v_cvt_pk_bf16_f32 v3, v20, v21
	s_add_u32 s0, s94, s0
	v_mad_u64_u32 v[8:9], s[8:9], v5, s33, v[2:3]
	ds_write_b32 v8, v3
	v_cvt_pk_bf16_f32 v3, v22, v23
	ds_write_b32 v8, v3 offset:4
	v_cvt_pk_bf16_f32 v3, v24, v25
	s_addc_u32 s1, s95, s1
	v_mad_u64_u32 v[8:9], s[8:9], v44, s33, v[2:3]
	ds_write_b32 v8, v3
	v_cvt_pk_bf16_f32 v3, v26, v27
	ds_write_b32 v8, v3 offset:4
	v_cvt_pk_bf16_f32 v3, v28, v29
	s_add_i32 s5, s5, s30
	v_mad_u64_u32 v[8:9], s[8:9], v45, s33, v[2:3]
	ds_write_b32 v8, v3
	v_cvt_pk_bf16_f32 v3, v30, v31
	ds_write_b32 v8, v3 offset:4
	v_cvt_pk_bf16_f32 v3, v32, v33
	s_nop 0
	v_mad_u64_u32 v[8:9], s[8:9], v46, s33, v[2:3]
	ds_write_b32 v8, v3
	v_cvt_pk_bf16_f32 v3, v34, v35
	ds_write_b32 v8, v3 offset:4
	s_waitcnt vmcnt(0)
	v_cvt_pk_bf16_f32 v5, v36, v37
	v_mad_u64_u32 v[2:3], s[8:9], v47, s33, v[2:3]
	ds_write_b32 v2, v5
	v_and_b32_e32 v5, 56, v48
	v_lshlrev_b32_e32 v194, 1, v5
	v_mul_u32_u24_e32 v5, 0x204, v5
	v_lshl_add_u32 v8, v7, 1, v5
	v_cvt_pk_bf16_f32 v3, v38, v39
	ds_write_b32 v2, v3 offset:4
	s_waitcnt lgkmcnt(0)
	s_barrier
	ds_read_u16 v12, v8
	ds_read_u16 v13, v8 offset:516
	ds_read_u16 v9, v8 offset:1032
	ds_read_u16 v14, v8 offset:1548
	ds_read_u16 v10, v8 offset:2064
	ds_read_u16 v15, v8 offset:2580
	ds_read_u16 v11, v8 offset:3096
	ds_read_u16 v8, v8 offset:3612
	v_subrev_u32_e32 v7, s6, v7
	v_lshl_add_u64 v[2:3], s[0:1], 0, v[194:195]
	s_waitcnt lgkmcnt(2)
	v_perm_b32 v10, v15, v10, s34
	v_perm_b32 v9, v14, v9, s34
	s_waitcnt lgkmcnt(0)
	v_perm_b32 v11, v8, v11, s34
	v_perm_b32 v8, v13, v12, s34
	v_add_u32_e32 v12, s4, v7
	v_ashrrev_i32_e32 v13, 31, v12
	v_lshlrev_b64 v[12:13], 12, v[12:13]
	v_lshl_add_u64 v[12:13], v[2:3], 0, v[12:13]
	v_ashrrev_i32_e32 v7, 3, v41
	global_store_dwordx4 v[12:13], v[8:11], off
	s_nop 1
	v_lshl_add_u32 v8, v7, 1, v5
	ds_read_u16 v12, v8
	ds_read_u16 v13, v8 offset:516
	ds_read_u16 v9, v8 offset:1032
	ds_read_u16 v14, v8 offset:1548
	ds_read_u16 v10, v8 offset:2064
	ds_read_u16 v15, v8 offset:2580
	ds_read_u16 v11, v8 offset:3096
	ds_read_u16 v8, v8 offset:3612
	v_subrev_u32_e32 v7, s6, v7
	s_waitcnt lgkmcnt(4)
	v_perm_b32 v9, v14, v9, s34
	s_waitcnt lgkmcnt(2)
	v_perm_b32 v10, v15, v10, s34
	s_waitcnt lgkmcnt(0)
	v_perm_b32 v11, v8, v11, s34
	v_perm_b32 v8, v13, v12, s34
	v_add_u32_e32 v12, s4, v7
	v_ashrrev_i32_e32 v13, 31, v12
	v_lshlrev_b64 v[12:13], 12, v[12:13]
	v_lshl_add_u64 v[12:13], v[2:3], 0, v[12:13]
	global_store_dwordx4 v[12:13], v[8:11], off
	s_nop 1
	v_ashrrev_i32_e32 v10, 3, v6
	v_lshl_add_u32 v6, v10, 1, v5
	ds_read_u16 v11, v6
	ds_read_u16 v12, v6 offset:516
	ds_read_u16 v7, v6 offset:1032
	ds_read_u16 v13, v6 offset:1548
	ds_read_u16 v8, v6 offset:2064
	ds_read_u16 v14, v6 offset:2580
	ds_read_u16 v9, v6 offset:3096
	ds_read_u16 v6, v6 offset:3612
	v_subrev_u32_e32 v10, s6, v10
	v_add_u32_e32 v10, s4, v10
	s_waitcnt lgkmcnt(2)
	v_perm_b32 v8, v14, v8, s34
	v_perm_b32 v7, v13, v7, s34
	s_waitcnt lgkmcnt(0)
	v_perm_b32 v9, v6, v9, s34
	v_perm_b32 v6, v12, v11, s34
	v_ashrrev_i32_e32 v11, 31, v10
	v_lshlrev_b64 v[10:11], 12, v[10:11]
	v_lshl_add_u64 v[10:11], v[2:3], 0, v[10:11]
	global_store_dwordx4 v[10:11], v[6:9], off
	s_nop 1
	v_ashrrev_i32_e32 v8, 3, v4
	v_lshl_add_u32 v4, v8, 1, v5
	ds_read_u16 v9, v4
	ds_read_u16 v10, v4 offset:516
	ds_read_u16 v5, v4 offset:1032
	ds_read_u16 v11, v4 offset:1548
	ds_read_u16 v6, v4 offset:2064
	ds_read_u16 v12, v4 offset:2580
	ds_read_u16 v7, v4 offset:3096
	ds_read_u16 v4, v4 offset:3612
	v_subrev_u32_e32 v8, s6, v8
	v_add_u32_e32 v8, s4, v8
	s_add_i32 s4, s4, s24
	s_waitcnt lgkmcnt(2)
	v_perm_b32 v6, v12, v6, s34
	s_waitcnt lgkmcnt(0)
	v_perm_b32 v7, v4, v7, s34
	v_perm_b32 v4, v10, v9, s34
	v_ashrrev_i32_e32 v9, 31, v8
	v_lshlrev_b64 v[8:9], 12, v[8:9]
	v_perm_b32 v5, v11, v5, s34
	v_lshl_add_u64 v[2:3], v[2:3], 0, v[8:9]
	s_cmpk_lt_i32 s5, 0x780
	global_store_dwordx4 v[2:3], v[4:7], off
	s_barrier
	s_cbranch_scc1 .LBB0_88
